# norm phases: the second row of a pair reuses the first row's shift/scale vectors when both rows have the same conditioning row (checked at run time)
# speedup vs baseline: 1.0070x; 1.0041x over previous
.LBB0_167:
	s_or_b64 exec, exec, s[14:15]
	v_add_u32_e32 v31, 0xffffe000, v40
	v_lshrrev_b32_e32 v31, 12, v31
	v_add_u32_e32 v31, 1, v31
	v_cmp_lt_i32_e32 vcc, s48, v40
	v_mov_b64_e32 v[70:71], s[4:5]
	s_waitcnt vmcnt(3)
	v_mov_b32_e32 v86, v21
	v_cndmask_b32_e32 v31, 0, v31, vcc
	v_add_u32_e32 v31, s69, v31
	v_mad_u64_u32 v[74:75], s[6:7], v31, s50, v[70:71]
	v_lshl_add_u64 v[82:83], v[74:75], 0, s[58:59]
	v_lshl_add_u64 v[84:85], v[74:75], 0, v[164:165]
	v_lshl_add_u64 v[78:79], v[82:83], 0, v[164:165]
	s_nop 0
	v_mov_b32_e32 v252, v78
	v_mov_b32_e32 v253, v79
	global_load_dwordx4 v[214:217], v[84:85], off
	global_load_dwordx4 v[218:221], v[84:85], off offset:1024
	global_load_dwordx4 v[222:225], v[84:85], off offset:2048
	global_load_dwordx4 v[226:229], v[84:85], off offset:3072
	global_load_dwordx4 v[230:233], v[252:253], off
	global_load_dwordx4 v[240:243], v[252:253], off offset:1024
	global_load_dwordx4 v[244:247], v[252:253], off offset:2048
	global_load_dwordx4 v[248:251], v[252:253], off offset:3072
	s_waitcnt vmcnt(0)
	v_mov_b32_e32 v70, v198
	v_mov_b32_e32 v71, v199
	v_mov_b32_e32 v72, v200
	v_mov_b32_e32 v73, v201
	v_mov_b32_e32 v74, v214
	v_mov_b32_e32 v75, v215
	v_mov_b32_e32 v76, v216
	v_mov_b32_e32 v77, v217
	v_mov_b32_e32 v78, v230
	v_mov_b32_e32 v79, v231
	v_mov_b32_e32 v80, v232
	v_mov_b32_e32 v81, v233
	v_mov_b32_e32 v87, v17
	v_mov_b32_e32 v68, v20
	v_mov_b32_e32 v69, v16
	v_pk_mul_f32 v[86:87], v[86:87], v[86:87]
	v_mov_b32_e32 v88, v22
	v_mov_b32_e32 v89, v18
	v_pk_fma_f32 v[68:69], v[68:69], v[68:69], v[86:87]
	v_mov_b32_e32 v90, v23
	v_pk_fma_f32 v[68:69], v[88:89], v[88:89], v[68:69]
	v_mov_b32_e32 v88, v13
	v_mov_b32_e32 v89, v9
	v_mov_b32_e32 v91, v19
	v_mov_b32_e32 v86, v12
	v_mov_b32_e32 v87, v8
	v_pk_mul_f32 v[88:89], v[88:89], v[88:89]
	v_pk_fma_f32 v[68:69], v[90:91], v[90:91], v[68:69]
	v_mov_b32_e32 v90, v14
	v_mov_b32_e32 v91, v10
	v_pk_fma_f32 v[86:87], v[86:87], v[86:87], v[88:89]
	v_mov_b32_e32 v92, v15
	v_mov_b32_e32 v93, v11
	v_pk_fma_f32 v[86:87], v[90:91], v[90:91], v[86:87]
	v_add_f32_e32 v31, v68, v69
	v_pk_fma_f32 v[86:87], v[92:93], v[92:93], v[86:87]
	v_lshlrev_b32_e32 v68, 2, v30
	v_add_f32_e32 v31, v31, v86
	v_add_f32_e32 v31, v31, v87
	ds_bpermute_b32 v33, v27, v31
	v_mov_b32_e32 v69, v165
	v_lshl_add_u64 v[86:87], v[82:83], 0, v[68:69]
	s_waitcnt lgkmcnt(0)
	v_add_f32_e32 v31, v31, v33
	ds_swizzle_b32 v33, v31 offset:swizzle(SWAP,16)
	s_waitcnt lgkmcnt(0)
	v_add_f32_e32 v31, v31, v33
	ds_swizzle_b32 v33, v31 offset:swizzle(SWAP,8)
	s_waitcnt lgkmcnt(0)
	v_add_f32_e32 v31, v31, v33
	ds_swizzle_b32 v33, v31 offset:swizzle(SWAP,4)
	s_waitcnt lgkmcnt(0)
	v_add_f32_e32 v31, v31, v33
	ds_swizzle_b32 v33, v31 offset:swizzle(SWAP,2)
	s_waitcnt lgkmcnt(0)
	v_add_f32_e32 v31, v31, v33
	ds_swizzle_b32 v33, v31 offset:swizzle(SWAP,1)
	s_waitcnt lgkmcnt(0)
	v_add_f32_e32 v31, v31, v33
	v_fmamk_f32 v31, v31, 0x3a800000, v189
	v_mul_f32_e32 v33, 0x4b800000, v31
	v_cmp_gt_f32_e32 vcc, s28, v31
	v_add_f32_e32 v35, 1.0, v79
	s_nop 0
	v_cndmask_b32_e32 v31, v31, v33, vcc
	v_rsq_f32_e32 v31, v31
	v_add_f32_e32 v41, 1.0, v80
	v_add_f32_e32 v51, 1.0, v81
	v_mul_f32_e32 v33, 0x45800000, v31
	v_cndmask_b32_e32 v31, v31, v33, vcc
	v_mul_f32_e32 v20, v20, v31
	v_mul_f32_e32 v21, v21, v31
	v_mul_f32_e32 v22, v22, v31
	v_mul_f32_e32 v23, v23, v31
	v_mul_f32_e32 v20, v70, v20
	v_mul_f32_e32 v21, v71, v21
	v_add_f32_e32 v33, 1.0, v78
	v_mul_f32_e32 v22, v72, v22
	v_mul_f32_e32 v23, v73, v23
	v_fma_f32 v20, v33, v20, v74
	v_fma_f32 v21, v35, v21, v75
	v_fma_f32 v22, v22, v41, v76
	v_fmac_f32_e32 v77, v23, v51
	v_cvt_pk_bf16_f32 v20, v20, v21
	v_cvt_pk_bf16_f32 v21, v22, v77
	global_store_dwordx2 v[38:39], v[20:21], off
	v_mov_b32_e32 v70, v202
	v_mov_b32_e32 v71, v203
	v_mov_b32_e32 v72, v204
	v_mov_b32_e32 v73, v205
	v_mov_b32_e32 v74, v240
	v_mov_b32_e32 v75, v241
	v_mov_b32_e32 v76, v242
	v_mov_b32_e32 v77, v243
	v_mov_b32_e32 v78, v218
	v_mov_b32_e32 v79, v219
	v_mov_b32_e32 v80, v220
	v_mov_b32_e32 v81, v221
	v_mul_f32_e32 v16, v16, v31
	v_mul_f32_e32 v17, v17, v31
	v_mul_f32_e32 v18, v18, v31
	v_mul_f32_e32 v19, v19, v31
	v_lshlrev_b32_e32 v20, 2, v32
	v_mov_b32_e32 v21, v165
	v_lshl_add_u64 v[22:23], v[82:83], 0, v[20:21]
	v_mul_f32_e32 v12, v12, v31
	v_mul_f32_e32 v13, v13, v31
	v_mul_f32_e32 v14, v14, v31
	v_mul_f32_e32 v15, v15, v31
	v_mul_f32_e32 v8, v8, v31
	v_mul_f32_e32 v9, v9, v31
	v_mul_f32_e32 v10, v10, v31
	v_mul_f32_e32 v11, v11, v31
	v_mul_f32_e32 v16, v16, v70
	v_add_f32_e32 v33, 1.0, v74
	v_mul_f32_e32 v17, v17, v71
	v_add_f32_e32 v35, 1.0, v75
	v_mul_f32_e32 v18, v18, v72
	v_add_f32_e32 v41, 1.0, v76
	v_mul_f32_e32 v19, v19, v73
	v_add_f32_e32 v51, 1.0, v77
	v_fma_f32 v16, v16, v33, v78
	v_fma_f32 v17, v17, v35, v79
	v_fma_f32 v18, v18, v41, v80
	v_fmac_f32_e32 v81, v19, v51
	v_cvt_pk_bf16_f32 v16, v16, v17
	v_cvt_pk_bf16_f32 v17, v18, v81
	global_store_dwordx2 v[38:39], v[16:17], off offset:512
	v_mov_b32_e32 v70, v206
	v_mov_b32_e32 v71, v207
	v_mov_b32_e32 v72, v208
	v_mov_b32_e32 v73, v209
	v_mov_b32_e32 v74, v244
	v_mov_b32_e32 v75, v245
	v_mov_b32_e32 v76, v246
	v_mov_b32_e32 v77, v247
	v_mov_b32_e32 v78, v222
	v_mov_b32_e32 v79, v223
	v_mov_b32_e32 v80, v224
	v_mov_b32_e32 v81, v225
	v_lshlrev_b32_e32 v16, 2, v34
	v_mov_b32_e32 v17, v165
	v_lshl_add_u64 v[18:19], v[82:83], 0, v[16:17]
	v_mul_f32_e32 v12, v12, v70
	v_add_f32_e32 v22, 1.0, v74
	v_mul_f32_e32 v13, v13, v71
	v_add_f32_e32 v23, 1.0, v75
	v_mul_f32_e32 v14, v14, v72
	v_add_f32_e32 v33, 1.0, v76
	v_mul_f32_e32 v15, v15, v73
	v_add_f32_e32 v35, 1.0, v77
	v_fma_f32 v12, v12, v22, v78
	v_fma_f32 v13, v13, v23, v79
	v_fma_f32 v14, v14, v33, v80
	v_fmac_f32_e32 v81, v15, v35
	v_cvt_pk_bf16_f32 v12, v12, v13
	v_cvt_pk_bf16_f32 v13, v14, v81
	global_store_dwordx2 v[38:39], v[12:13], off offset:1024
	v_mov_b32_e32 v12, v210
	v_mov_b32_e32 v13, v211
	v_mov_b32_e32 v14, v212
	v_mov_b32_e32 v15, v213
	s_nop 0
	v_mov_b32_e32 v70, v248
	v_mov_b32_e32 v71, v249
	v_mov_b32_e32 v72, v250
	v_mov_b32_e32 v73, v251
	v_mov_b32_e32 v74, v226
	v_mov_b32_e32 v75, v227
	v_mov_b32_e32 v76, v228
	v_mov_b32_e32 v77, v229
	v_mul_f32_e32 v8, v8, v12
	v_add_f32_e32 v12, 1.0, v70
	v_mul_f32_e32 v9, v9, v13
	v_add_f32_e32 v13, 1.0, v71
	v_mul_f32_e32 v10, v10, v14
	v_add_f32_e32 v14, 1.0, v72
	v_mul_f32_e32 v11, v11, v15
	v_add_f32_e32 v15, 1.0, v73
	v_fma_f32 v8, v8, v12, v74
	v_fma_f32 v9, v9, v13, v75
	v_fma_f32 v10, v10, v14, v76
	v_fmac_f32_e32 v77, v11, v15
	v_cvt_pk_bf16_f32 v8, v8, v9
	v_cvt_pk_bf16_f32 v9, v10, v77
	global_store_dwordx2 v[38:39], v[8:9], off offset:1536
	s_and_saveexec_b64 s[14:15], s[34:35]
	s_cbranch_execz .LBB0_148
	v_add_u32_e32 v8, 0xffffe000, v50
	v_lshrrev_b32_e32 v8, 12, v8
	v_add_u32_e32 v8, 1, v8
	v_cmp_lt_i32_e32 vcc, s48, v50
	v_mov_b64_e32 v[12:13], s[4:5]
	v_pk_mul_f32 v[60:61], v[60:61], v[60:61]
	v_cndmask_b32_e32 v8, 0, v8, vcc
	v_add_u32_e32 v14, s69, v8
	v_mad_u64_u32 v[18:19], s[6:7], v14, s50, v[12:13]
	v_lshl_add_u64 v[22:23], v[18:19], 0, s[58:59]
	v_lshl_add_u64 v[12:13], v[22:23], 0, v[164:165]
	v_lshl_add_u64 v[74:75], v[18:19], 0, v[164:165]
	v_pk_mul_f32 v[18:19], v[66:67], v[66:67]
	v_mov_b32_e32 v254, v12
	v_mov_b32_e32 v255, v13
	v_cmp_ne_u64_e32 vcc, v[254:255], v[252:253]
	s_nop 1
	s_and_b64 vcc, exec, vcc
	s_cbranch_vccz .Lnorm_same_cond_1
	global_load_dwordx4 v[214:217], v[74:75], off
	global_load_dwordx4 v[218:221], v[74:75], off offset:1024
	global_load_dwordx4 v[222:225], v[74:75], off offset:2048
	global_load_dwordx4 v[226:229], v[74:75], off offset:3072
	global_load_dwordx4 v[230:233], v[254:255], off
	global_load_dwordx4 v[240:243], v[254:255], off offset:1024
	global_load_dwordx4 v[244:247], v[254:255], off offset:2048
	global_load_dwordx4 v[248:251], v[254:255], off offset:3072
.Lnorm_same_cond_1:
	s_waitcnt vmcnt(0)
	v_mov_b32_e32 v8, v198
	v_mov_b32_e32 v9, v199
	v_mov_b32_e32 v10, v200
	v_mov_b32_e32 v11, v201
	v_mov_b32_e32 v12, v230
	v_mov_b32_e32 v13, v231
	v_mov_b32_e32 v14, v232
	v_mov_b32_e32 v15, v233
	v_mov_b32_e32 v70, v214
	v_mov_b32_e32 v71, v215
	v_mov_b32_e32 v72, v216
	v_mov_b32_e32 v73, v217
	v_pk_fma_f32 v[18:19], v[64:65], v[64:65], v[18:19]
	v_pk_fma_f32 v[56:57], v[56:57], v[56:57], v[60:61]
	v_pk_fma_f32 v[18:19], v[62:63], v[62:63], v[18:19]
	v_pk_fma_f32 v[54:55], v[54:55], v[54:55], v[56:57]
	v_pk_fma_f32 v[18:19], v[58:59], v[58:59], v[18:19]
	v_pk_fma_f32 v[52:53], v[52:53], v[52:53], v[54:55]
	v_add_f32_e32 v18, v18, v19
	v_add_f32_e32 v18, v53, v18
	v_add_f32_e32 v18, v52, v18
	ds_bpermute_b32 v19, v27, v18
	v_ashrrev_i32_e32 v51, 31, v50
	v_lshl_add_u64 v[16:17], v[22:23], 0, v[16:17]
	s_waitcnt lgkmcnt(0)
	v_add_f32_e32 v18, v18, v19
	ds_swizzle_b32 v19, v18 offset:swizzle(SWAP,16)
	s_waitcnt lgkmcnt(0)
	v_add_f32_e32 v18, v18, v19
	ds_swizzle_b32 v19, v18 offset:swizzle(SWAP,8)
	s_waitcnt lgkmcnt(0)
	v_add_f32_e32 v18, v18, v19
	ds_swizzle_b32 v19, v18 offset:swizzle(SWAP,4)
	s_waitcnt lgkmcnt(0)
	v_add_f32_e32 v18, v18, v19
	ds_swizzle_b32 v19, v18 offset:swizzle(SWAP,2)
	s_waitcnt lgkmcnt(0)
	v_add_f32_e32 v18, v18, v19
	ds_swizzle_b32 v19, v18 offset:swizzle(SWAP,1)
	s_waitcnt lgkmcnt(0)
	v_add_f32_e32 v18, v18, v19
	v_fmamk_f32 v18, v18, 0x3a800000, v189
	v_mul_f32_e32 v19, 0x4b800000, v18
	v_cmp_gt_f32_e32 vcc, s28, v18
	v_add_f32_e32 v12, 1.0, v12
	s_nop 0
	v_cndmask_b32_e32 v18, v18, v19, vcc
	v_rsq_f32_e32 v31, v18
	v_lshlrev_b64 v[18:19], 11, v[50:51]
	v_add_f32_e32 v13, 1.0, v13
	v_lshl_add_u64 v[54:55], v[36:37], 0, v[18:19]
	v_mul_f32_e32 v33, 0x45800000, v31
	v_cndmask_b32_e32 v31, v31, v33, vcc
	v_mul_f32_e32 v33, v49, v31
	v_mul_f32_e32 v35, v5, v31
	v_mul_f32_e32 v41, v47, v31
	v_mul_f32_e32 v50, v7, v31
	v_mul_f32_e32 v8, v8, v33
	v_mul_f32_e32 v9, v9, v35
	v_mul_f32_e32 v10, v10, v41
	v_mul_f32_e32 v11, v11, v50
	v_add_f32_e32 v14, 1.0, v14
	v_add_f32_e32 v15, 1.0, v15
	v_fma_f32 v8, v12, v8, v70
	v_fma_f32 v9, v13, v9, v71
	v_fma_f32 v10, v10, v14, v72
	v_fmac_f32_e32 v73, v11, v15
	v_cvt_pk_bf16_f32 v8, v8, v9
	v_cvt_pk_bf16_f32 v9, v10, v73
	global_store_dwordx2 v[54:55], v[8:9], off
	v_lshl_add_u64 v[18:19], v[22:23], 0, v[68:69]
	v_mov_b32_e32 v8, v202
	v_mov_b32_e32 v9, v203
	v_mov_b32_e32 v10, v204
	v_mov_b32_e32 v11, v205
	v_mov_b32_e32 v12, v240
	v_mov_b32_e32 v13, v241
	v_mov_b32_e32 v14, v242
	v_mov_b32_e32 v15, v243
	v_mov_b32_e32 v50, v218
	v_mov_b32_e32 v51, v219
	v_mov_b32_e32 v52, v220
	v_mov_b32_e32 v53, v221
	v_lshl_add_u64 v[18:19], v[22:23], 0, v[20:21]
	v_mul_f32_e32 v20, v48, v31
	v_mul_f32_e32 v21, v4, v31
	v_mul_f32_e32 v33, v46, v31
	v_mul_f32_e32 v35, v6, v31
	v_mul_f32_e32 v22, v45, v31
	v_mul_f32_e32 v23, v1, v31
	v_mul_f32_e32 v8, v20, v8
	v_add_f32_e32 v12, 1.0, v12
	v_mul_f32_e32 v9, v21, v9
	v_add_f32_e32 v13, 1.0, v13
	v_mul_f32_e32 v10, v33, v10
	v_add_f32_e32 v14, 1.0, v14
	v_mul_f32_e32 v11, v35, v11
	v_add_f32_e32 v15, 1.0, v15
	v_fma_f32 v8, v8, v12, v50
	v_fma_f32 v9, v9, v13, v51
	v_fma_f32 v10, v10, v14, v52
	v_fmac_f32_e32 v53, v11, v15
	v_cvt_pk_bf16_f32 v8, v8, v9
	v_cvt_pk_bf16_f32 v9, v10, v53
	global_store_dwordx2 v[54:55], v[8:9], off offset:512
	v_mov_b32_e32 v8, v206
	v_mov_b32_e32 v9, v207
	v_mov_b32_e32 v10, v208
	v_mov_b32_e32 v11, v209
	s_nop 0
	v_mov_b32_e32 v12, v244
	v_mov_b32_e32 v13, v245
	v_mov_b32_e32 v14, v246
	v_mov_b32_e32 v15, v247
	s_nop 0
	v_mov_b32_e32 v18, v222
	v_mov_b32_e32 v19, v223
	v_mov_b32_e32 v20, v224
	v_mov_b32_e32 v21, v225
	v_mul_f32_e32 v33, v43, v31
	v_mul_f32_e32 v35, v3, v31
	v_mul_f32_e32 v8, v22, v8
	v_add_f32_e32 v12, 1.0, v12
	v_mul_f32_e32 v9, v23, v9
	v_add_f32_e32 v13, 1.0, v13
	v_mul_f32_e32 v10, v33, v10
	v_add_f32_e32 v14, 1.0, v14
	v_mul_f32_e32 v11, v35, v11
	v_add_f32_e32 v15, 1.0, v15
	v_fma_f32 v8, v8, v12, v18
	v_fma_f32 v9, v9, v13, v19
	v_fma_f32 v10, v10, v14, v20
	v_fmac_f32_e32 v21, v11, v15
	v_cvt_pk_bf16_f32 v8, v8, v9
	v_cvt_pk_bf16_f32 v9, v10, v21
	global_store_dwordx2 v[54:55], v[8:9], off offset:1024
	v_mov_b32_e32 v8, v210
	v_mov_b32_e32 v9, v211
	v_mov_b32_e32 v10, v212
	v_mov_b32_e32 v11, v213
	s_nop 0
	v_mov_b32_e32 v12, v248
	v_mov_b32_e32 v13, v249
	v_mov_b32_e32 v14, v250
	v_mov_b32_e32 v15, v251
	s_nop 0
	v_mov_b32_e32 v16, v226
	v_mov_b32_e32 v17, v227
	v_mov_b32_e32 v18, v228
	v_mov_b32_e32 v19, v229
	v_mul_f32_e32 v20, v44, v31
	v_mul_f32_e32 v21, v0, v31
	v_mul_f32_e32 v22, v42, v31
	v_mul_f32_e32 v23, v2, v31
	v_mul_f32_e32 v8, v20, v8
	v_add_f32_e32 v12, 1.0, v12
	v_mul_f32_e32 v9, v21, v9
	v_add_f32_e32 v13, 1.0, v13
	v_mul_f32_e32 v10, v22, v10
	v_add_f32_e32 v14, 1.0, v14
	v_mul_f32_e32 v11, v23, v11
	v_add_f32_e32 v15, 1.0, v15
	v_fma_f32 v8, v8, v12, v16
	v_fma_f32 v9, v9, v13, v17
	v_fma_f32 v10, v10, v14, v18
	v_fmac_f32_e32 v19, v11, v15
	v_cvt_pk_bf16_f32 v8, v8, v9
	v_cvt_pk_bf16_f32 v9, v10, v19
	global_store_dwordx2 v[54:55], v[8:9], off offset:1536
	s_branch .LBB0_148

.LBB0_1334:
	s_or_b64 exec, exec, s[10:11]
	s_waitcnt vmcnt(3)
	v_mov_b32_e32 v26, v21
	s_waitcnt vmcnt(2)
	v_mov_b32_e32 v27, v17
	v_mov_b32_e32 v24, v20
	v_mov_b32_e32 v25, v16
	v_pk_mul_f32 v[26:27], v[26:27], v[26:27]
	v_mov_b32_e32 v78, v22
	v_mov_b32_e32 v79, v18
	v_pk_fma_f32 v[24:25], v[24:25], v[24:25], v[26:27]
	v_mov_b32_e32 v80, v23
	v_pk_fma_f32 v[24:25], v[78:79], v[78:79], v[24:25]
	s_waitcnt vmcnt(1)
	v_mov_b32_e32 v78, v13
	s_waitcnt vmcnt(0)
	v_mov_b32_e32 v79, v9
	v_mov_b32_e32 v81, v19
	v_mov_b32_e32 v26, v12
	v_mov_b32_e32 v27, v8
	v_pk_mul_f32 v[78:79], v[78:79], v[78:79]
	v_pk_fma_f32 v[24:25], v[80:81], v[80:81], v[24:25]
	v_mov_b32_e32 v80, v14
	v_mov_b32_e32 v81, v10
	v_pk_fma_f32 v[26:27], v[26:27], v[26:27], v[78:79]
	v_mov_b32_e32 v82, v15
	v_mov_b32_e32 v83, v11
	v_pk_fma_f32 v[26:27], v[80:81], v[80:81], v[26:27]
	v_add_f32_e32 v24, v24, v25
	v_pk_fma_f32 v[26:27], v[82:83], v[82:83], v[26:27]
	s_nop 0
	v_add_f32_e32 v24, v24, v26
	v_add_f32_e32 v24, v24, v27
	ds_bpermute_b32 v25, v31, v24
	s_waitcnt lgkmcnt(0)
	v_add_f32_e32 v24, v24, v25
	ds_swizzle_b32 v25, v24 offset:swizzle(SWAP,16)
	s_waitcnt lgkmcnt(0)
	v_add_f32_e32 v24, v24, v25
	ds_swizzle_b32 v25, v24 offset:swizzle(SWAP,8)
	s_waitcnt lgkmcnt(0)
	v_add_f32_e32 v24, v24, v25
	ds_swizzle_b32 v25, v24 offset:swizzle(SWAP,4)
	s_waitcnt lgkmcnt(0)
	v_add_f32_e32 v24, v24, v25
	ds_swizzle_b32 v25, v24 offset:swizzle(SWAP,2)
	s_waitcnt lgkmcnt(0)
	v_add_f32_e32 v24, v24, v25
	ds_swizzle_b32 v25, v24 offset:swizzle(SWAP,1)
	s_waitcnt lgkmcnt(0)
	v_add_f32_e32 v24, v24, v25
	v_fmamk_f32 v24, v24, 0x3a800000, v189
	v_cmp_gt_f32_e64 s[34:35], s28, v24
	v_mul_f32_e32 v25, 0x4b800000, v24
	s_nop 0
	v_cndmask_b32_e64 v24, v24, v25, s[34:35]
	v_rsq_f32_e32 v24, v24
	s_nop 0
	v_mul_f32_e32 v25, 0x45800000, v24
	v_cndmask_b32_e64 v29, v24, v25, s[34:35]
	v_add_u32_e32 v24, 0xffffe000, v28
	v_lshrrev_b32_e32 v24, 12, v24
	v_add_u32_e32 v24, 1, v24
	v_cmp_lt_i32_e64 s[34:35], s48, v28
	v_mul_f32_e32 v20, v20, v29
	v_mul_f32_e32 v21, v21, v29
	v_cndmask_b32_e64 v24, 0, v24, s[34:35]
	v_add_u32_e32 v26, s86, v24
	v_mov_b64_e32 v[24:25], s[4:5]
	v_mad_u64_u32 v[78:79], s[6:7], v26, s50, v[24:25]
	v_lshl_add_u64 v[80:81], v[78:79], 0, s[58:59]
	v_lshl_add_u64 v[82:83], v[78:79], 0, v[164:165]
	v_lshl_add_u64 v[78:79], v[80:81], 0, v[164:165]
	v_mov_b32_e32 v252, v78
	v_mov_b32_e32 v253, v79
	global_load_dwordx4 v[214:217], v[82:83], off
	global_load_dwordx4 v[218:221], v[82:83], off offset:1024
	global_load_dwordx4 v[222:225], v[82:83], off offset:2048
	global_load_dwordx4 v[226:229], v[82:83], off offset:3072
	global_load_dwordx4 v[230:233], v[252:253], off
	global_load_dwordx4 v[240:243], v[252:253], off offset:1024
	global_load_dwordx4 v[244:247], v[252:253], off offset:2048
	global_load_dwordx4 v[248:251], v[252:253], off offset:3072
	s_waitcnt vmcnt(0)
	v_mov_b32_e32 v24, v198
	v_mov_b32_e32 v25, v199
	v_mov_b32_e32 v26, v200
	v_mov_b32_e32 v27, v201
	v_mov_b32_e32 v84, v214
	v_mov_b32_e32 v85, v215
	v_mov_b32_e32 v86, v216
	v_mov_b32_e32 v87, v217
	v_mov_b32_e32 v88, v230
	v_mov_b32_e32 v89, v231
	v_mov_b32_e32 v90, v232
	v_mov_b32_e32 v91, v233
	v_mul_f32_e32 v22, v22, v29
	v_mul_f32_e32 v23, v23, v29
	v_lshlrev_b32_e32 v78, 2, v34
	v_mov_b32_e32 v79, v165
	v_mul_f32_e32 v16, v16, v29
	v_mul_f32_e32 v17, v17, v29
	v_mul_f32_e32 v18, v18, v29
	v_mul_f32_e32 v19, v19, v29
	v_mul_f32_e32 v12, v12, v29
	v_mul_f32_e32 v13, v13, v29
	v_mul_f32_e32 v14, v14, v29
	v_mul_f32_e32 v15, v15, v29
	v_mul_f32_e32 v8, v8, v29
	v_mul_f32_e32 v9, v9, v29
	v_mul_f32_e32 v10, v10, v29
	v_mul_f32_e32 v11, v11, v29
	v_mul_f32_e32 v20, v24, v20
	v_mul_f32_e32 v21, v25, v21
	v_add_f32_e32 v24, 1.0, v88
	v_fma_f32 v20, v24, v20, v84
	v_add_f32_e32 v24, 1.0, v89
	v_fma_f32 v21, v24, v21, v85
	v_mul_f32_e32 v22, v26, v22
	v_add_f32_e32 v24, 1.0, v90
	v_fma_f32 v22, v22, v24, v86
	v_mul_f32_e32 v23, v27, v23
	v_add_f32_e32 v24, 1.0, v91
	v_fmac_f32_e32 v87, v23, v24
	v_cvt_pk_bf16_f32 v20, v20, v21
	v_cvt_pk_bf16_f32 v21, v22, v87
	global_store_dwordx2 v[48:49], v[20:21], off
	v_lshl_add_u64 v[84:85], v[80:81], 0, v[78:79]
	v_mov_b32_e32 v24, v202
	v_mov_b32_e32 v25, v203
	v_mov_b32_e32 v26, v204
	v_mov_b32_e32 v27, v205
	v_mov_b32_e32 v20, v218
	v_mov_b32_e32 v21, v219
	v_mov_b32_e32 v22, v220
	v_mov_b32_e32 v23, v221
	v_mul_f32_e32 v16, v16, v24
	v_mov_b32_e32 v84, v240
	v_mov_b32_e32 v85, v241
	v_mov_b32_e32 v86, v242
	v_mov_b32_e32 v87, v243
	v_mul_f32_e32 v17, v17, v25
	v_mul_f32_e32 v18, v18, v26
	v_mul_f32_e32 v19, v19, v27
	v_add_f32_e32 v24, 1.0, v84
	v_fma_f32 v16, v16, v24, v20
	v_add_f32_e32 v20, 1.0, v85
	v_fma_f32 v17, v17, v20, v21
	v_add_f32_e32 v20, 1.0, v86
	v_fma_f32 v18, v18, v20, v22
	v_add_f32_e32 v20, 1.0, v87
	v_fmac_f32_e32 v23, v19, v20
	v_lshlrev_b32_e32 v20, 2, v38
	v_mov_b32_e32 v21, v165
	v_cvt_pk_bf16_f32 v16, v16, v17
	v_cvt_pk_bf16_f32 v17, v18, v23
	global_store_dwordx2 v[48:49], v[16:17], off offset:512
	v_lshl_add_u64 v[26:27], v[80:81], 0, v[20:21]
	v_mov_b32_e32 v16, v206
	v_mov_b32_e32 v17, v207
	v_mov_b32_e32 v18, v208
	v_mov_b32_e32 v19, v209
	v_mov_b32_e32 v22, v222
	v_mov_b32_e32 v23, v223
	v_mov_b32_e32 v24, v224
	v_mov_b32_e32 v25, v225
	v_mov_b32_e32 v84, v244
	v_mov_b32_e32 v85, v245
	v_mov_b32_e32 v86, v246
	v_mov_b32_e32 v87, v247
	v_mul_f32_e32 v12, v12, v16
	v_mul_f32_e32 v13, v13, v17
	v_add_f32_e32 v16, 1.0, v84
	v_fma_f32 v12, v12, v16, v22
	v_add_f32_e32 v16, 1.0, v85
	v_fma_f32 v13, v13, v16, v23
	v_mul_f32_e32 v14, v14, v18
	v_add_f32_e32 v16, 1.0, v86
	v_fma_f32 v14, v14, v16, v24
	v_mul_f32_e32 v15, v15, v19
	v_add_f32_e32 v16, 1.0, v87
	v_fmac_f32_e32 v25, v15, v16
	v_lshlrev_b32_e32 v22, 2, v42
	v_mov_b32_e32 v23, v165
	v_cvt_pk_bf16_f32 v12, v12, v13
	v_cvt_pk_bf16_f32 v13, v14, v25
	global_store_dwordx2 v[48:49], v[12:13], off offset:1024
	v_lshl_add_u64 v[24:25], v[80:81], 0, v[22:23]
	v_mov_b32_e32 v16, v210
	v_mov_b32_e32 v17, v211
	v_mov_b32_e32 v18, v212
	v_mov_b32_e32 v19, v213
	v_mov_b32_e32 v12, v226
	v_mov_b32_e32 v13, v227
	v_mov_b32_e32 v14, v228
	v_mov_b32_e32 v15, v229
	v_mul_f32_e32 v8, v8, v16
	v_mov_b32_e32 v24, v248
	v_mov_b32_e32 v25, v249
	v_mov_b32_e32 v26, v250
	v_mov_b32_e32 v27, v251
	v_mul_f32_e32 v9, v9, v17
	v_mul_f32_e32 v10, v10, v18
	v_mul_f32_e32 v11, v11, v19
	v_add_f32_e32 v16, 1.0, v24
	v_fma_f32 v8, v8, v16, v12
	v_add_f32_e32 v12, 1.0, v25
	v_fma_f32 v9, v9, v12, v13
	v_add_f32_e32 v12, 1.0, v26
	v_fma_f32 v10, v10, v12, v14
	v_add_f32_e32 v12, 1.0, v27
	v_fmac_f32_e32 v15, v11, v12
	v_cvt_pk_bf16_f32 v8, v8, v9
	v_cvt_pk_bf16_f32 v9, v10, v15
	global_store_dwordx2 v[48:49], v[8:9], off offset:1536
	s_and_saveexec_b64 s[10:11], vcc
	s_cbranch_execz .LBB0_1331
	v_pk_mul_f32 v[8:9], v[76:77], v[76:77]
	v_pk_mul_f32 v[10:11], v[68:69], v[68:69]
	v_pk_fma_f32 v[8:9], v[74:75], v[74:75], v[8:9]
	v_pk_fma_f32 v[10:11], v[66:67], v[66:67], v[10:11]
	v_pk_fma_f32 v[8:9], v[72:73], v[72:73], v[8:9]
	v_pk_fma_f32 v[10:11], v[64:65], v[64:65], v[10:11]
	v_pk_fma_f32 v[8:9], v[70:71], v[70:71], v[8:9]
	v_pk_fma_f32 v[10:11], v[62:63], v[62:63], v[10:11]
	v_add_f32_e32 v8, v8, v9
	v_add_f32_e32 v8, v11, v8
	v_add_f32_e32 v8, v10, v8
	ds_bpermute_b32 v9, v31, v8
	v_lshlrev_b64 v[14:15], 11, v[60:61]
	s_waitcnt lgkmcnt(0)
	v_add_f32_e32 v8, v8, v9
	ds_swizzle_b32 v9, v8 offset:swizzle(SWAP,16)
	s_waitcnt lgkmcnt(0)
	v_add_f32_e32 v8, v8, v9
	ds_swizzle_b32 v9, v8 offset:swizzle(SWAP,8)
	s_waitcnt lgkmcnt(0)
	v_add_f32_e32 v8, v8, v9
	ds_swizzle_b32 v9, v8 offset:swizzle(SWAP,4)
	s_waitcnt lgkmcnt(0)
	v_add_f32_e32 v8, v8, v9
	ds_swizzle_b32 v9, v8 offset:swizzle(SWAP,2)
	s_waitcnt lgkmcnt(0)
	v_add_f32_e32 v8, v8, v9
	ds_swizzle_b32 v9, v8 offset:swizzle(SWAP,1)
	s_waitcnt lgkmcnt(0)
	v_add_f32_e32 v8, v8, v9
	v_fmamk_f32 v8, v8, 0x3a800000, v189
	v_cmp_gt_f32_e32 vcc, s28, v8
	v_mul_f32_e32 v9, 0x4b800000, v8
	s_nop 0
	v_cndmask_b32_e32 v8, v8, v9, vcc
	v_rsq_f32_e32 v8, v8
	s_nop 0
	v_mul_f32_e32 v9, 0x45800000, v8
	v_cndmask_b32_e32 v24, v8, v9, vcc
	v_add_u32_e32 v8, 0xffffe000, v60
	v_lshrrev_b32_e32 v8, 12, v8
	v_add_u32_e32 v8, 1, v8
	v_cmp_lt_i32_e32 vcc, s48, v60
	s_nop 1
	v_cndmask_b32_e32 v8, 0, v8, vcc
	v_add_u32_e32 v10, s86, v8
	v_mov_b64_e32 v[8:9], s[4:5]
	v_mad_u64_u32 v[8:9], s[6:7], v10, s50, v[8:9]
	v_lshl_add_u64 v[16:17], v[8:9], 0, s[58:59]
	v_lshl_add_u64 v[8:9], v[8:9], 0, v[164:165]
	v_lshl_add_u64 v[18:19], v[16:17], 0, v[164:165]
	v_mov_b32_e32 v254, v18
	v_mov_b32_e32 v255, v19
	v_cmp_ne_u64_e32 vcc, v[254:255], v[252:253]
	s_nop 1
	s_and_b64 vcc, exec, vcc
	s_cbranch_vccz .Lnorm_same_cond_2
	global_load_dwordx4 v[214:217], v[8:9], off
	global_load_dwordx4 v[218:221], v[8:9], off offset:1024
	global_load_dwordx4 v[222:225], v[8:9], off offset:2048
	global_load_dwordx4 v[226:229], v[8:9], off offset:3072
	global_load_dwordx4 v[230:233], v[254:255], off
	global_load_dwordx4 v[240:243], v[254:255], off offset:1024
	global_load_dwordx4 v[244:247], v[254:255], off offset:2048
	global_load_dwordx4 v[248:251], v[254:255], off offset:3072
.Lnorm_same_cond_2:
	s_waitcnt vmcnt(0)
	v_mov_b32_e32 v10, v198
	v_mov_b32_e32 v11, v199
	v_mov_b32_e32 v12, v200
	v_mov_b32_e32 v13, v201
	v_mov_b32_e32 v60, v214
	v_mov_b32_e32 v61, v215
	v_mov_b32_e32 v62, v216
	v_mov_b32_e32 v63, v217
	v_mov_b32_e32 v64, v230
	v_mov_b32_e32 v65, v231
	v_mov_b32_e32 v66, v232
	v_mov_b32_e32 v67, v233
	v_mul_f32_e32 v18, v5, v24
	v_mul_f32_e32 v10, v10, v18
	v_add_f32_e32 v18, 1.0, v64
	v_fma_f32 v10, v18, v10, v60
	v_mul_f32_e32 v18, v59, v24
	v_mul_f32_e32 v11, v11, v18
	v_add_f32_e32 v18, 1.0, v65
	v_fma_f32 v11, v18, v11, v61
	v_mul_f32_e32 v18, v7, v24
	v_mul_f32_e32 v12, v12, v18
	v_add_f32_e32 v18, 1.0, v66
	v_fma_f32 v12, v12, v18, v62
	v_mul_f32_e32 v18, v57, v24
	v_mul_f32_e32 v13, v13, v18
	v_add_f32_e32 v18, 1.0, v67
	v_fmac_f32_e32 v63, v13, v18
	v_lshl_add_u64 v[18:19], v[46:47], 0, v[14:15]
	v_cvt_pk_bf16_f32 v10, v10, v11
	v_cvt_pk_bf16_f32 v11, v12, v63
	global_store_dwordx2 v[18:19], v[10:11], off
	v_lshl_add_u64 v[14:15], v[16:17], 0, v[78:79]
	v_mov_b32_e32 v10, v202
	v_mov_b32_e32 v11, v203
	v_mov_b32_e32 v12, v204
	v_mov_b32_e32 v13, v205
	v_mov_b32_e32 v60, v218
	v_mov_b32_e32 v61, v219
	v_mov_b32_e32 v62, v220
	v_mov_b32_e32 v63, v221
	v_mov_b32_e32 v64, v240
	v_mov_b32_e32 v65, v241
	v_mov_b32_e32 v66, v242
	v_mov_b32_e32 v67, v243
	v_mul_f32_e32 v14, v4, v24
	v_mul_f32_e32 v10, v14, v10
	v_add_f32_e32 v14, 1.0, v64
	v_fma_f32 v10, v10, v14, v60
	v_mul_f32_e32 v14, v58, v24
	v_mul_f32_e32 v11, v14, v11
	v_add_f32_e32 v14, 1.0, v65
	v_fma_f32 v11, v11, v14, v61
	v_mul_f32_e32 v14, v6, v24
	v_mul_f32_e32 v12, v14, v12
	v_add_f32_e32 v14, 1.0, v66
	v_fma_f32 v12, v12, v14, v62
	v_mul_f32_e32 v14, v56, v24
	v_mul_f32_e32 v13, v14, v13
	v_add_f32_e32 v14, 1.0, v67
	v_fmac_f32_e32 v63, v13, v14
	v_cvt_pk_bf16_f32 v10, v10, v11
	v_cvt_pk_bf16_f32 v11, v12, v63
	global_store_dwordx2 v[18:19], v[10:11], off offset:512
	v_lshl_add_u64 v[14:15], v[16:17], 0, v[20:21]
	v_mov_b32_e32 v10, v206
	v_mov_b32_e32 v11, v207
	v_mov_b32_e32 v12, v208
	v_mov_b32_e32 v13, v209
	v_mov_b32_e32 v60, v222
	v_mov_b32_e32 v61, v223
	v_mov_b32_e32 v62, v224
	v_mov_b32_e32 v63, v225
	v_mov_b32_e32 v64, v244
	v_mov_b32_e32 v65, v245
	v_mov_b32_e32 v66, v246
	v_mov_b32_e32 v67, v247
	v_mul_f32_e32 v14, v1, v24
	v_lshl_add_u64 v[16:17], v[16:17], 0, v[22:23]
	v_mul_f32_e32 v10, v14, v10
	v_add_f32_e32 v14, 1.0, v64
	v_fma_f32 v10, v10, v14, v60
	v_mul_f32_e32 v14, v55, v24
	v_mul_f32_e32 v11, v14, v11
	v_add_f32_e32 v14, 1.0, v65
	v_fma_f32 v11, v11, v14, v61
	v_mul_f32_e32 v14, v3, v24
	v_mul_f32_e32 v12, v14, v12
	v_add_f32_e32 v14, 1.0, v66
	v_fma_f32 v12, v12, v14, v62
	v_mul_f32_e32 v14, v53, v24
	v_mul_f32_e32 v13, v14, v13
	v_add_f32_e32 v14, 1.0, v67
	v_fmac_f32_e32 v63, v13, v14
	v_cvt_pk_bf16_f32 v10, v10, v11
	v_cvt_pk_bf16_f32 v11, v12, v63
	global_store_dwordx2 v[18:19], v[10:11], off offset:1024
	v_mov_b32_e32 v12, v210
	v_mov_b32_e32 v13, v211
	v_mov_b32_e32 v14, v212
	v_mov_b32_e32 v15, v213
	s_nop 0
	v_mov_b32_e32 v8, v226
	v_mov_b32_e32 v9, v227
	v_mov_b32_e32 v10, v228
	v_mov_b32_e32 v11, v229
	s_nop 0
	v_mov_b32_e32 v20, v248
	v_mov_b32_e32 v21, v249
	v_mov_b32_e32 v22, v250
	v_mov_b32_e32 v23, v251
	v_mul_f32_e32 v16, v0, v24
	v_mul_f32_e32 v12, v16, v12
	v_add_f32_e32 v16, 1.0, v20
	v_fma_f32 v8, v12, v16, v8
	v_mul_f32_e32 v12, v54, v24
	v_mul_f32_e32 v12, v12, v13
	v_add_f32_e32 v13, 1.0, v21
	v_fma_f32 v9, v12, v13, v9
	v_mul_f32_e32 v12, v2, v24
	v_mul_f32_e32 v12, v12, v14
	v_add_f32_e32 v13, 1.0, v22
	v_fma_f32 v10, v12, v13, v10
	v_mul_f32_e32 v12, v52, v24
	v_mul_f32_e32 v12, v12, v15
	v_add_f32_e32 v13, 1.0, v23
	v_fmac_f32_e32 v11, v12, v13
	v_cvt_pk_bf16_f32 v8, v8, v9
	v_cvt_pk_bf16_f32 v9, v10, v11
	global_store_dwordx2 v[18:19], v[8:9], off offset:1536
	s_branch .LBB0_1331
